# gate/up K loop: 8 ping-pong phases merged pairwise into 4 (32 MFMAs per section, 8 barriers per iteration instead of 16; stages into just-read buffers issued one section later; LDS reads drained befor
# speedup vs baseline: 1.0133x; 1.0133x over previous
; #define PG8_STAGE(bufoff, gbase, voff) do { _Pragma("unroll") for (int _i = 0; _i < 2; ++_i) \
;     __builtin_amdgcn_global_load_lds((const unsigned*)((const char*)(gbase) + (voff)[_i]), (LAS unsigned*)(lds + (bufoff) + ldsw + _i * 8192), 16, 0, 0); } while (0)
; #define PG8_LDA(dst, b, h) do { _Pragma("unroll") for (int m = 0; m < 4; ++m) _Pragma("unroll") for (int k = 0; k < 2; ++k) dst[m][k] = *(const LAS bf16x8*)(lds + PG8_SA(b, h) + aoff + m * 2048 + k * 1024); } while (0)
; #define PG8_LDB(dst, b, h) do { _Pragma("unroll") for (int n = 0; n < 2; ++n) _Pragma("unroll") for (int k = 0; k < 2; ++k) dst[n][k] = *(const LAS bf16x8*)(lds + PG8_SB(b, h) + boff + n * 2048 + k * 1024); } while (0)
; #define PG8_MMA(ai, bj, At, Bt) do { __builtin_amdgcn_s_setprio(1); _Pragma("unroll") for (int m = 0; m < 4; ++m) _Pragma("unroll") for (int n = 0; n < 2; ++n) _Pragma("unroll") for (int k = 0; k < 2; ++k) \
;     acc[ai][bj][m][n] = __builtin_amdgcn_mfma_f32_16x16x32_bf16(Bt[n][k], At[m][k], acc[ai][bj][m][n], 0, 0, 0); __builtin_amdgcn_s_setprio(0); } while (0)
; #define PG8_WAIT_V(n) asm volatile("s_waitcnt vmcnt(" #n ")" ::: "memory")
; #define PG8_WAIT_L(n) asm volatile("s_waitcnt lgkmcnt(" #n ")" ::: "memory")
; #define PG8_BAR __builtin_amdgcn_s_barrier()
; #define PG8_SCHED __builtin_amdgcn_sched_barrier(0)
; template <class Epi, class Sched>
; DI void gemm_phase(LAS unsigned char* lds, const Gemm g, const Sched& S, const Epi& E) {
;     ...
;       PG8_LDB(B0, 0, 0); PG8_SCHED; PG8_LDA(At, 0, 0); PG8_STAGE(PG8_SA(1, 1), a1 + hstep, voffA);
;       PG8_WAIT_L(8); PG8_BAR; PG8_WAIT_L(0); PG8_MMA(0, 0, At, B0); PG8_BAR; PG8_SCHED;
;       PG8_LDB(B1, 0, 1); PG8_STAGE(PG8_SB(0, 0), b2, voffB);
;       PG8_BAR; PG8_WAIT_L(0); PG8_MMA(0, 1, At, B1); PG8_BAR;
;       PG8_LDA(At, 0, 1); PG8_STAGE(PG8_SA(0, 0), a2, voffA);
;       PG8_BAR; PG8_WAIT_L(0); PG8_MMA(1, 0, At, B0); PG8_BAR; PG8_SCHED;
;       PG8_STAGE(PG8_SB(0, 1), b2 + hstepB, voffB);
;       PG8_WAIT_V(6); PG8_BAR; PG8_MMA(1, 1, At, B1); PG8_BAR;
.LBB0_178:
	s_add_i32 s51, s24, 2
	s_add_u32 s26, s22, 0x80
	s_addc_u32 s25, s23, 0
	s_add_i32 s52, 16, 0x10000
	v_add_u32_e32 v156, s52, v141
	ds_read_b128 v[144:147], v156
	ds_read_b128 v[148:151], v156 offset:1024
	ds_read_b128 v[152:155], v156 offset:2048
	ds_read_b128 v[156:159], v156 offset:3072
	s_cmp_eq_u32 s43, s24
	s_cselect_b32 s24, s18, s26
	s_cselect_b32 s25, s19, s25
	s_cselect_b32 s27, s21, s50
	s_cselect_b32 s26, s20, s49
	v_lshl_add_u64 v[176:177], s[22:23], 0, v[136:137]
	s_add_i32 m0, s36, 0xc000
	ds_read_b128 v[160:163], v143
	ds_read_b128 v[164:167], v143 offset:1024
	ds_read_b128 v[168:171], v143 offset:2048
	ds_read_b128 v[172:175], v143 offset:3072
	ds_read_b128 v[186:189], v143 offset:4096
	ds_read_b128 v[190:193], v143 offset:5120
	ds_read_b128 v[198:201], v143 offset:6144
	ds_read_b128 v[202:205], v143 offset:7168
	global_load_lds_dwordx4 v[176:177], off
	v_lshl_add_u64 v[176:177], s[22:23], 0, v[138:139]
	s_add_i32 m0, s36, 0xe000
	s_nop 0
	global_load_lds_dwordx4 v[176:177], off
	s_add_i32 s53, 16, 0x14000
	v_add_u32_e32 v176, s53, v141
	s_add_i32 s52, s52, s35
	ds_read_b128 v[206:209], v176
	ds_read_b128 v[214:217], v176 offset:1024
	ds_read_b128 v[218:221], v176 offset:2048
	ds_read_b128 v[222:225], v176 offset:3072
	s_waitcnt lgkmcnt(0)
	s_barrier
	v_mfma_f32_16x16x32_bf16 v[122:125], v[144:147], v[160:163], v[122:125]
	v_mfma_f32_16x16x32_bf16 v[118:121], v[152:155], v[160:163], v[118:121]
	v_mfma_f32_16x16x32_bf16 v[110:113], v[144:147], v[168:171], v[110:113]
	v_mfma_f32_16x16x32_bf16 v[102:105], v[152:155], v[168:171], v[102:105]
	v_mfma_f32_16x16x32_bf16 v[94:97], v[144:147], v[186:189], v[94:97]
	v_mfma_f32_16x16x32_bf16 v[86:89], v[152:155], v[186:189], v[86:89]
	v_mfma_f32_16x16x32_bf16 v[78:81], v[144:147], v[198:201], v[78:81]
	v_mfma_f32_16x16x32_bf16 v[70:73], v[152:155], v[198:201], v[70:73]
	v_mfma_f32_16x16x32_bf16 v[122:125], v[148:151], v[164:167], v[122:125]
	v_mfma_f32_16x16x32_bf16 v[118:121], v[156:159], v[164:167], v[118:121]
	v_mfma_f32_16x16x32_bf16 v[110:113], v[148:151], v[172:175], v[110:113]
	v_mfma_f32_16x16x32_bf16 v[102:105], v[156:159], v[172:175], v[102:105]
	v_mfma_f32_16x16x32_bf16 v[94:97], v[148:151], v[190:193], v[94:97]
	v_mfma_f32_16x16x32_bf16 v[86:89], v[156:159], v[190:193], v[86:89]
	v_mfma_f32_16x16x32_bf16 v[78:81], v[148:151], v[202:205], v[78:81]
	v_mfma_f32_16x16x32_bf16 v[70:73], v[156:159], v[202:205], v[70:73]
	v_mfma_f32_16x16x32_bf16 v[126:129], v[206:209], v[160:163], v[126:129]
	v_mfma_f32_16x16x32_bf16 v[114:117], v[218:221], v[160:163], v[114:117]
	v_mfma_f32_16x16x32_bf16 v[106:109], v[206:209], v[168:171], v[106:109]
	v_mfma_f32_16x16x32_bf16 v[98:101], v[218:221], v[168:171], v[98:101]
	v_mfma_f32_16x16x32_bf16 v[90:93], v[206:209], v[186:189], v[90:93]
	v_mfma_f32_16x16x32_bf16 v[82:85], v[218:221], v[186:189], v[82:85]
	v_mfma_f32_16x16x32_bf16 v[74:77], v[206:209], v[198:201], v[74:77]
	v_mfma_f32_16x16x32_bf16 v[66:69], v[218:221], v[198:201], v[66:69]
	v_mfma_f32_16x16x32_bf16 v[126:129], v[214:217], v[164:167], v[126:129]
	v_mfma_f32_16x16x32_bf16 v[114:117], v[222:225], v[164:167], v[114:117]
	v_mfma_f32_16x16x32_bf16 v[106:109], v[214:217], v[172:175], v[106:109]
	v_mfma_f32_16x16x32_bf16 v[98:101], v[222:225], v[172:175], v[98:101]
	v_mfma_f32_16x16x32_bf16 v[90:93], v[214:217], v[190:193], v[90:93]
	v_mfma_f32_16x16x32_bf16 v[82:85], v[222:225], v[190:193], v[82:85]
	v_mfma_f32_16x16x32_bf16 v[74:77], v[214:217], v[202:205], v[74:77]
	v_mfma_f32_16x16x32_bf16 v[66:69], v[222:225], v[202:205], v[66:69]
	s_mov_b32 m0, s36
	v_lshl_add_u64 v[182:183], s[24:25], 0, v[134:135]
	s_barrier
	ds_read_b128 v[160:163], v143 offset:16384
	ds_read_b128 v[164:167], v143 offset:17408
	ds_read_b128 v[168:171], v143 offset:18432
	ds_read_b128 v[172:175], v143 offset:19456
	ds_read_b128 v[186:189], v143 offset:20480
	ds_read_b128 v[190:193], v143 offset:21504
	ds_read_b128 v[198:201], v143 offset:22528
	ds_read_b128 v[202:205], v143 offset:23552
	global_load_lds_dwordx4 v[182:183], off
	v_lshl_add_u64 v[184:185], s[24:25], 0, v[132:133]
	s_mov_b32 m0, s37
	s_nop 0
	global_load_lds_dwordx4 v[184:185], off
	v_lshl_add_u64 v[230:231], s[26:27], 0, v[0:1]
	s_mov_b32 m0, s52
	v_lshl_add_u64 v[180:181], s[26:27], 0, v[130:131]
	global_load_lds_dwordx4 v[230:231], off
	s_add_i32 m0, s52, 0x2000
	s_nop 0
	global_load_lds_dwordx4 v[180:181], off
	s_add_u32 s26, s26, s0
	s_addc_u32 s27, s27, s1
	s_add_i32 s52, s53, s35
	v_lshl_add_u64 v[226:227], s[26:27], 0, v[0:1]
	s_mov_b32 m0, s52
	v_lshl_add_u64 v[228:229], s[26:27], 0, v[130:131]
	global_load_lds_dwordx4 v[226:227], off
	s_add_i32 m0, s52, 0x2000
	s_nop 0
	global_load_lds_dwordx4 v[228:229], off
	s_waitcnt vmcnt(6)
	s_waitcnt lgkmcnt(0)
	s_barrier
; #define PG8_STAGE(bufoff, gbase, voff) do { _Pragma("unroll") for (int _i = 0; _i < 2; ++_i) \
;     __builtin_amdgcn_global_load_lds((const unsigned*)((const char*)(gbase) + (voff)[_i]), (LAS unsigned*)(lds + (bufoff) + ldsw + _i * 8192), 16, 0, 0); } while (0)
; #define PG8_LDA(dst, b, h) do { _Pragma("unroll") for (int m = 0; m < 4; ++m) _Pragma("unroll") for (int k = 0; k < 2; ++k) dst[m][k] = *(const LAS bf16x8*)(lds + PG8_SA(b, h) + aoff + m * 2048 + k * 1024); } while (0)
; #define PG8_LDB(dst, b, h) do { _Pragma("unroll") for (int n = 0; n < 2; ++n) _Pragma("unroll") for (int k = 0; k < 2; ++k) dst[n][k] = *(const LAS bf16x8*)(lds + PG8_SB(b, h) + boff + n * 2048 + k * 1024); } while (0)
; #define PG8_MMA(ai, bj, At, Bt) do { __builtin_amdgcn_s_setprio(1); _Pragma("unroll") for (int m = 0; m < 4; ++m) _Pragma("unroll") for (int n = 0; n < 2; ++n) _Pragma("unroll") for (int k = 0; k < 2; ++k) \
;     acc[ai][bj][m][n] = __builtin_amdgcn_mfma_f32_16x16x32_bf16(Bt[n][k], At[m][k], acc[ai][bj][m][n], 0, 0, 0); __builtin_amdgcn_s_setprio(0); } while (0)
; #define PG8_WAIT_V(n) asm volatile("s_waitcnt vmcnt(" #n ")" ::: "memory")
; #define PG8_WAIT_L(n) asm volatile("s_waitcnt lgkmcnt(" #n ")" ::: "memory")
; #define PG8_BAR __builtin_amdgcn_s_barrier()
; #define PG8_SCHED __builtin_amdgcn_sched_barrier(0)
; template <class Epi, class Sched>
; DI void gemm_phase(LAS unsigned char* lds, const Gemm g, const Sched& S, const Epi& E) {
;     ...
;       PG8_WAIT_V(6); PG8_BAR; PG8_MMA(1, 1, At, B1); PG8_BAR;
;       PG8_LDB(B0, 1, 0); PG8_SCHED; PG8_LDA(At, 1, 0); PG8_STAGE(PG8_SA(0, 1), a2 + hstep, voffA);
;       PG8_WAIT_L(8); PG8_BAR; PG8_WAIT_L(0); PG8_MMA(0, 0, At, B0); PG8_BAR; PG8_SCHED;
;       PG8_LDB(B1, 1, 1); PG8_STAGE(PG8_SB(1, 0), b3, voffB);
;       PG8_BAR; PG8_WAIT_L(0); PG8_MMA(0, 1, At, B1); PG8_BAR;
;       PG8_LDA(At, 1, 1); PG8_STAGE(PG8_SA(1, 0), a3, voffA);
;       PG8_BAR; PG8_WAIT_L(0); PG8_MMA(1, 0, At, B0); PG8_BAR; PG8_SCHED;
	v_mfma_f32_16x16x32_bf16 v[62:65], v[144:147], v[160:163], v[62:65]
	v_mfma_f32_16x16x32_bf16 v[54:57], v[152:155], v[160:163], v[54:57]
	v_mfma_f32_16x16x32_bf16 v[46:49], v[144:147], v[168:171], v[46:49]
	v_mfma_f32_16x16x32_bf16 v[38:41], v[152:155], v[168:171], v[38:41]
	v_mfma_f32_16x16x32_bf16 v[30:33], v[144:147], v[186:189], v[30:33]
	v_mfma_f32_16x16x32_bf16 v[22:25], v[152:155], v[186:189], v[22:25]
	v_mfma_f32_16x16x32_bf16 v[14:17], v[144:147], v[198:201], v[14:17]
	v_mfma_f32_16x16x32_bf16 v[6:9], v[152:155], v[198:201], v[6:9]
	v_mfma_f32_16x16x32_bf16 v[62:65], v[148:151], v[164:167], v[62:65]
	v_mfma_f32_16x16x32_bf16 v[54:57], v[156:159], v[164:167], v[54:57]
	v_mfma_f32_16x16x32_bf16 v[46:49], v[148:151], v[172:175], v[46:49]
	v_mfma_f32_16x16x32_bf16 v[38:41], v[156:159], v[172:175], v[38:41]
	v_mfma_f32_16x16x32_bf16 v[30:33], v[148:151], v[190:193], v[30:33]
	v_mfma_f32_16x16x32_bf16 v[22:25], v[156:159], v[190:193], v[22:25]
	v_mfma_f32_16x16x32_bf16 v[14:17], v[148:151], v[202:205], v[14:17]
	v_mfma_f32_16x16x32_bf16 v[6:9], v[156:159], v[202:205], v[6:9]
	v_mfma_f32_16x16x32_bf16 v[58:61], v[206:209], v[160:163], v[58:61]
	v_mfma_f32_16x16x32_bf16 v[50:53], v[218:221], v[160:163], v[50:53]
	v_mfma_f32_16x16x32_bf16 v[42:45], v[206:209], v[168:171], v[42:45]
	v_mfma_f32_16x16x32_bf16 v[34:37], v[218:221], v[168:171], v[34:37]
	v_mfma_f32_16x16x32_bf16 v[26:29], v[206:209], v[186:189], v[26:29]
	v_mfma_f32_16x16x32_bf16 v[18:21], v[218:221], v[186:189], v[18:21]
	v_mfma_f32_16x16x32_bf16 v[10:13], v[206:209], v[198:201], v[10:13]
	v_mfma_f32_16x16x32_bf16 v[2:5], v[218:221], v[198:201], v[2:5]
	v_mfma_f32_16x16x32_bf16 v[58:61], v[214:217], v[164:167], v[58:61]
	v_mfma_f32_16x16x32_bf16 v[50:53], v[222:225], v[164:167], v[50:53]
	v_mfma_f32_16x16x32_bf16 v[42:45], v[214:217], v[172:175], v[42:45]
	v_mfma_f32_16x16x32_bf16 v[34:37], v[222:225], v[172:175], v[34:37]
	v_mfma_f32_16x16x32_bf16 v[26:29], v[214:217], v[190:193], v[26:29]
	v_mfma_f32_16x16x32_bf16 v[18:21], v[222:225], v[190:193], v[18:21]
	v_mfma_f32_16x16x32_bf16 v[10:13], v[214:217], v[202:205], v[10:13]
	v_mfma_f32_16x16x32_bf16 v[2:5], v[222:225], v[202:205], v[2:5]
	s_add_i32 s26, 16, 0x18000
	v_add_u32_e32 v156, s26, v141
	s_barrier
	ds_read_b128 v[144:147], v156
	ds_read_b128 v[148:151], v156 offset:1024
	ds_read_b128 v[152:155], v156 offset:2048
	ds_read_b128 v[156:159], v156 offset:3072
	s_add_u32 s24, s24, s0
	s_addc_u32 s25, s25, s1
	s_mov_b32 m0, s38
	v_lshl_add_u64 v[206:207], s[24:25], 0, v[134:135]
	ds_read_b128 v[160:163], v143 offset:32768
	ds_read_b128 v[164:167], v143 offset:33792
	ds_read_b128 v[168:171], v143 offset:34816
	ds_read_b128 v[172:175], v143 offset:35840
	ds_read_b128 v[186:189], v143 offset:36864
	ds_read_b128 v[190:193], v143 offset:37888
	ds_read_b128 v[198:201], v143 offset:38912
	ds_read_b128 v[202:205], v143 offset:39936
	global_load_lds_dwordx4 v[206:207], off
	v_lshl_add_u64 v[206:207], s[24:25], 0, v[132:133]
	s_mov_b32 m0, s39
	s_nop 0
	global_load_lds_dwordx4 v[206:207], off
	s_add_i32 s24, 16, 0x1c000
	s_add_i32 s25, s26, s35
	v_add_u32_e32 v194, s24, v141
	ds_read_b128 v[206:209], v194
	ds_read_b128 v[214:217], v194 offset:1024
	ds_read_b128 v[218:221], v194 offset:2048
	ds_read_b128 v[222:225], v194 offset:3072
	s_waitcnt lgkmcnt(0)
	s_barrier
	v_mfma_f32_16x16x32_bf16 v[122:125], v[144:147], v[160:163], v[122:125]
	v_mfma_f32_16x16x32_bf16 v[118:121], v[152:155], v[160:163], v[118:121]
	v_mfma_f32_16x16x32_bf16 v[110:113], v[144:147], v[168:171], v[110:113]
	v_mfma_f32_16x16x32_bf16 v[102:105], v[152:155], v[168:171], v[102:105]
	v_mfma_f32_16x16x32_bf16 v[94:97], v[144:147], v[186:189], v[94:97]
	v_mfma_f32_16x16x32_bf16 v[86:89], v[152:155], v[186:189], v[86:89]
	v_mfma_f32_16x16x32_bf16 v[78:81], v[144:147], v[198:201], v[78:81]
	v_mfma_f32_16x16x32_bf16 v[70:73], v[152:155], v[198:201], v[70:73]
	v_mfma_f32_16x16x32_bf16 v[122:125], v[148:151], v[164:167], v[122:125]
	v_mfma_f32_16x16x32_bf16 v[118:121], v[156:159], v[164:167], v[118:121]
	v_mfma_f32_16x16x32_bf16 v[110:113], v[148:151], v[172:175], v[110:113]
	v_mfma_f32_16x16x32_bf16 v[102:105], v[156:159], v[172:175], v[102:105]
	v_mfma_f32_16x16x32_bf16 v[94:97], v[148:151], v[190:193], v[94:97]
	v_mfma_f32_16x16x32_bf16 v[86:89], v[156:159], v[190:193], v[86:89]
	v_mfma_f32_16x16x32_bf16 v[78:81], v[148:151], v[202:205], v[78:81]
	v_mfma_f32_16x16x32_bf16 v[70:73], v[156:159], v[202:205], v[70:73]
	v_mfma_f32_16x16x32_bf16 v[126:129], v[206:209], v[160:163], v[126:129]
	v_mfma_f32_16x16x32_bf16 v[114:117], v[218:221], v[160:163], v[114:117]
	v_mfma_f32_16x16x32_bf16 v[106:109], v[206:209], v[168:171], v[106:109]
	v_mfma_f32_16x16x32_bf16 v[98:101], v[218:221], v[168:171], v[98:101]
	v_mfma_f32_16x16x32_bf16 v[90:93], v[206:209], v[186:189], v[90:93]
	v_mfma_f32_16x16x32_bf16 v[82:85], v[218:221], v[186:189], v[82:85]
	v_mfma_f32_16x16x32_bf16 v[74:77], v[206:209], v[198:201], v[74:77]
	v_mfma_f32_16x16x32_bf16 v[66:69], v[218:221], v[198:201], v[66:69]
	v_mfma_f32_16x16x32_bf16 v[126:129], v[214:217], v[164:167], v[126:129]
	v_mfma_f32_16x16x32_bf16 v[114:117], v[222:225], v[164:167], v[114:117]
	v_mfma_f32_16x16x32_bf16 v[106:109], v[214:217], v[172:175], v[106:109]
	v_mfma_f32_16x16x32_bf16 v[98:101], v[222:225], v[172:175], v[98:101]
	v_mfma_f32_16x16x32_bf16 v[90:93], v[214:217], v[190:193], v[90:93]
	v_mfma_f32_16x16x32_bf16 v[82:85], v[222:225], v[190:193], v[82:85]
	v_mfma_f32_16x16x32_bf16 v[74:77], v[214:217], v[202:205], v[74:77]
	v_mfma_f32_16x16x32_bf16 v[66:69], v[222:225], v[202:205], v[66:69]
	s_mov_b32 m0, s41
	v_lshl_add_u64 v[176:177], v[182:183], 0, s[70:71]
	s_barrier
; #define PG8_STAGE(bufoff, gbase, voff) do { _Pragma("unroll") for (int _i = 0; _i < 2; ++_i) \
;     __builtin_amdgcn_global_load_lds((const unsigned*)((const char*)(gbase) + (voff)[_i]), (LAS unsigned*)(lds + (bufoff) + ldsw + _i * 8192), 16, 0, 0); } while (0)
; #define PG8_LDA(dst, b, h) do { _Pragma("unroll") for (int m = 0; m < 4; ++m) _Pragma("unroll") for (int k = 0; k < 2; ++k) dst[m][k] = *(const LAS bf16x8*)(lds + PG8_SA(b, h) + aoff + m * 2048 + k * 1024); } while (0)
; #define PG8_MMA(ai, bj, At, Bt) do { __builtin_amdgcn_s_setprio(1); _Pragma("unroll") for (int m = 0; m < 4; ++m) _Pragma("unroll") for (int n = 0; n < 2; ++n) _Pragma("unroll") for (int k = 0; k < 2; ++k) \
;     acc[ai][bj][m][n] = __builtin_amdgcn_mfma_f32_16x16x32_bf16(Bt[n][k], At[m][k], acc[ai][bj][m][n], 0, 0, 0); __builtin_amdgcn_s_setprio(0); } while (0)
; #define PG8_WAIT_V(n) asm volatile("s_waitcnt vmcnt(" #n ")" ::: "memory")
; #define PG8_WAIT_L(n) asm volatile("s_waitcnt lgkmcnt(" #n ")" ::: "memory")
; #define PG8_BAR __builtin_amdgcn_s_barrier()
; #define PG8_SCHED __builtin_amdgcn_sched_barrier(0)
; template <class Epi, class Sched>
; DI void gemm_phase(LAS unsigned char* lds, const Gemm g, const Sched& S, const Epi& E) {
;     ...
;       PG8_LDA(At, 1, 1); PG8_STAGE(PG8_SA(1, 0), a3, voffA);
;       PG8_BAR; PG8_WAIT_L(0); PG8_MMA(1, 0, At, B0); PG8_BAR; PG8_SCHED;
;       PG8_STAGE(PG8_SB(1, 1), b3 + hstepB, voffB);
;       PG8_WAIT_V(6); PG8_BAR; PG8_MMA(1, 1, At, B1); PG8_BAR;
;     }
	ds_read_b128 v[160:163], v143 offset:49152
	ds_read_b128 v[164:167], v143 offset:50176
	ds_read_b128 v[168:171], v143 offset:51200
	ds_read_b128 v[172:175], v143 offset:52224
	ds_read_b128 v[186:189], v143 offset:53248
	ds_read_b128 v[190:193], v143 offset:54272
	ds_read_b128 v[198:201], v143 offset:55296
	ds_read_b128 v[202:205], v143 offset:56320
	global_load_lds_dwordx4 v[176:177], off
	v_lshl_add_u64 v[176:177], v[184:185], 0, s[70:71]
	s_mov_b32 m0, s42
	s_nop 0
	global_load_lds_dwordx4 v[176:177], off
	s_mov_b32 m0, s25
	v_lshl_add_u64 v[230:231], v[230:231], 0, s[70:71]
	global_load_lds_dwordx4 v[230:231], off
	v_lshl_add_u64 v[176:177], v[180:181], 0, s[70:71]
	s_add_i32 m0, s25, 0x2000
	s_nop 0
	global_load_lds_dwordx4 v[176:177], off
	s_add_i32 s24, s24, s35
	v_lshl_add_u64 v[232:233], v[226:227], 0, s[70:71]
	s_mov_b32 m0, s24
	s_nop 0
	global_load_lds_dwordx4 v[232:233], off
	v_lshl_add_u64 v[232:233], v[228:229], 0, s[70:71]
	s_add_i32 m0, s24, 0x2000
	s_nop 0
	global_load_lds_dwordx4 v[232:233], off
	s_waitcnt vmcnt(6)
	s_waitcnt lgkmcnt(0)
	s_barrier
	v_mfma_f32_16x16x32_bf16 v[62:65], v[144:147], v[160:163], v[62:65]
	v_mfma_f32_16x16x32_bf16 v[54:57], v[152:155], v[160:163], v[54:57]
	v_mfma_f32_16x16x32_bf16 v[46:49], v[144:147], v[168:171], v[46:49]
	v_mfma_f32_16x16x32_bf16 v[38:41], v[152:155], v[168:171], v[38:41]
	v_mfma_f32_16x16x32_bf16 v[30:33], v[144:147], v[186:189], v[30:33]
	v_mfma_f32_16x16x32_bf16 v[22:25], v[152:155], v[186:189], v[22:25]
	v_mfma_f32_16x16x32_bf16 v[14:17], v[144:147], v[198:201], v[14:17]
	v_mfma_f32_16x16x32_bf16 v[6:9], v[152:155], v[198:201], v[6:9]
	v_mfma_f32_16x16x32_bf16 v[62:65], v[148:151], v[164:167], v[62:65]
	v_mfma_f32_16x16x32_bf16 v[54:57], v[156:159], v[164:167], v[54:57]
	v_mfma_f32_16x16x32_bf16 v[46:49], v[148:151], v[172:175], v[46:49]
	v_mfma_f32_16x16x32_bf16 v[38:41], v[156:159], v[172:175], v[38:41]
	v_mfma_f32_16x16x32_bf16 v[30:33], v[148:151], v[190:193], v[30:33]
	v_mfma_f32_16x16x32_bf16 v[22:25], v[156:159], v[190:193], v[22:25]
	v_mfma_f32_16x16x32_bf16 v[14:17], v[148:151], v[202:205], v[14:17]
	v_mfma_f32_16x16x32_bf16 v[6:9], v[156:159], v[202:205], v[6:9]
	v_mfma_f32_16x16x32_bf16 v[58:61], v[206:209], v[160:163], v[58:61]
	v_mfma_f32_16x16x32_bf16 v[50:53], v[218:221], v[160:163], v[50:53]
	v_mfma_f32_16x16x32_bf16 v[42:45], v[206:209], v[168:171], v[42:45]
	v_mfma_f32_16x16x32_bf16 v[34:37], v[218:221], v[168:171], v[34:37]
	v_mfma_f32_16x16x32_bf16 v[26:29], v[206:209], v[186:189], v[26:29]
	v_mfma_f32_16x16x32_bf16 v[18:21], v[218:221], v[186:189], v[18:21]
	v_mfma_f32_16x16x32_bf16 v[10:13], v[206:209], v[198:201], v[10:13]
	v_mfma_f32_16x16x32_bf16 v[2:5], v[218:221], v[198:201], v[2:5]
	v_mfma_f32_16x16x32_bf16 v[58:61], v[214:217], v[164:167], v[58:61]
	v_mfma_f32_16x16x32_bf16 v[50:53], v[222:225], v[164:167], v[50:53]
	v_mfma_f32_16x16x32_bf16 v[42:45], v[214:217], v[172:175], v[42:45]
	v_mfma_f32_16x16x32_bf16 v[34:37], v[222:225], v[172:175], v[34:37]
	v_mfma_f32_16x16x32_bf16 v[26:29], v[214:217], v[190:193], v[26:29]
	v_mfma_f32_16x16x32_bf16 v[18:21], v[222:225], v[190:193], v[18:21]
	v_mfma_f32_16x16x32_bf16 v[10:13], v[214:217], v[202:205], v[10:13]
	v_mfma_f32_16x16x32_bf16 v[2:5], v[222:225], v[202:205], v[2:5]
	s_add_u32 s22, s22, 0x100
	s_addc_u32 s23, s23, 0
	s_add_u32 s49, s49, 0x100
	s_addc_u32 s50, s50, 0
	s_cmp_ge_i32 s51, s40
	s_mov_b32 s24, s51
	s_barrier
	s_cbranch_scc0 .LBB0_178
	s_branch .LBB0_161
